# P0: I_UQ (kscale) and I_IN transpose items rewritten with all 32 loads batched before LDS writes; kscale multiply moved after LDS transpose (same f32 mul)
# speedup vs baseline: 1.0125x; 1.0089x over previous
; #define LAS __attribute__((address_space(3)))
; __device__ __forceinline__ unsigned cvt_pk_bf16(float lo, float hi) { unsigned r; asm("v_cvt_pk_bf16_f32 %0, %1, %2" : "=v"(r) : "v"(lo), "v"(hi)); return r; }
; #define LDS_WAIT() asm volatile("s_waitcnt lgkmcnt(0)" ::: "memory")
; __device__ __forceinline__ void p0_transpose_item(const float* W, int ldw, int c0, int k0, bf16_t* WT, int K, int n0, const float* kscale, LAS float* scr, int lane) {
;     ...
;     const int c = lane & 7;
; #pragma unroll
;     for (int j = 0; j < 4; ++j) { const int n = (lane >> 3) + 8 * j; const LAS float* s = scr + (8 * c) * 33 + n;
;         u32x4 o; o.x = cvt_pk_bf16(s[0 * 33], s[1 * 33]); o.y = cvt_pk_bf16(s[2 * 33], s[3 * 33]); o.z = cvt_pk_bf16(s[4 * 33], s[5 * 33]); o.w = cvt_pk_bf16(s[6 * 33], s[7 * 33]);
;         *(u32x4*)(WT + (size_t)(n0 + n) * K + k0 + 8 * c) = o; }
;     LDS_WAIT(); asm volatile("" ::: "memory");
.LBB0_20:
	s_waitcnt lgkmcnt(0)
	s_ashr_i32 s1, s0, 31
	ds_read2_b32 v[40:41], v62 offset0:33 offset1:41
	ds_read2_b32 v[110:111], v62 offset1:8
	ds_read2_b32 v[112:113], v62 offset0:66 offset1:74
	ds_read2_b32 v[114:115], v62 offset0:99 offset1:107
	ds_read2_b32 v[116:117], v62 offset0:132 offset1:140
	ds_read2_b32 v[118:119], v62 offset0:165 offset1:173
	ds_read2_b32 v[120:121], v62 offset0:198 offset1:206
	ds_read2_b32 v[122:123], v62 offset0:231 offset1:239
	v_lshl_add_u64 v[124:125], s[0:1], 1, v[38:39]
	s_add_i32 s0, s22, s19
	v_add_u32_e32 v126, s0, v42
	v_ashrrev_i32_e32 v127, 31, v126
	v_lshlrev_b64 v[128:129], 11, v[126:127]
	s_waitcnt lgkmcnt(6)
	v_cvt_pk_bf16_f32 v106, v110, v40
	v_lshl_add_u64 v[128:129], v[124:125], 0, v[128:129]
	v_add_u32_e32 v40, 8, v126
	s_waitcnt lgkmcnt(4)
	v_cvt_pk_bf16_f32 v107, v112, v114
	s_waitcnt lgkmcnt(2)
	v_cvt_pk_bf16_f32 v108, v116, v118
	s_waitcnt lgkmcnt(0)
	v_cvt_pk_bf16_f32 v109, v120, v122
	global_store_dwordx4 v[128:129], v[106:109], off
	s_nop 1
	v_cvt_pk_bf16_f32 v106, v111, v41
	v_ashrrev_i32_e32 v41, 31, v40
	v_lshlrev_b64 v[40:41], 11, v[40:41]
	v_cvt_pk_bf16_f32 v107, v113, v115
	v_cvt_pk_bf16_f32 v108, v117, v119
	v_cvt_pk_bf16_f32 v109, v121, v123
	v_lshl_add_u64 v[40:41], v[124:125], 0, v[40:41]
	ds_read2_b32 v[110:111], v62 offset0:16 offset1:24
	ds_read2_b32 v[112:113], v62 offset0:49 offset1:57
	ds_read2_b32 v[114:115], v62 offset0:82 offset1:90
	ds_read2_b32 v[116:117], v62 offset0:115 offset1:123
	ds_read2_b32 v[118:119], v62 offset0:148 offset1:156
	ds_read2_b32 v[120:121], v62 offset0:181 offset1:189
	ds_read2_b32 v[122:123], v62 offset0:214 offset1:222
	ds_read2_b32 v[128:129], v62 offset0:247 offset1:255
	global_store_dwordx4 v[40:41], v[106:109], off
	v_add_u32_e32 v40, 16, v126
	v_ashrrev_i32_e32 v41, 31, v40
	v_lshlrev_b64 v[40:41], 11, v[40:41]
	v_lshl_add_u64 v[40:41], v[124:125], 0, v[40:41]
	s_waitcnt lgkmcnt(6)
	v_cvt_pk_bf16_f32 v106, v110, v112
	s_waitcnt lgkmcnt(4)
	v_cvt_pk_bf16_f32 v107, v114, v116
	s_waitcnt lgkmcnt(2)
	v_cvt_pk_bf16_f32 v108, v118, v120
	s_waitcnt lgkmcnt(0)
	v_cvt_pk_bf16_f32 v109, v122, v128
	global_store_dwordx4 v[40:41], v[106:109], off
	v_add_u32_e32 v40, 24, v126
	v_ashrrev_i32_e32 v41, 31, v40
	v_lshlrev_b64 v[40:41], 11, v[40:41]
	v_lshl_add_u64 v[40:41], v[124:125], 0, v[40:41]
	v_cvt_pk_bf16_f32 v106, v111, v113
	v_cvt_pk_bf16_f32 v107, v115, v117
	v_cvt_pk_bf16_f32 v108, v119, v121
	v_cvt_pk_bf16_f32 v109, v123, v129
	global_store_dwordx4 v[40:41], v[106:109], off
	s_waitcnt lgkmcnt(0)

; #define LAS __attribute__((address_space(3)))
; __device__ __forceinline__ void p0_transpose_item(const float* W, int ldw, int c0, int k0, bf16_t* WT, int K, int n0, const float* kscale, LAS float* scr, int lane) {
; #pragma unroll
;     for (int i = 0; i < 32; ++i) { const int kk = 2 * i + (lane >> 5); float v = 0.f;
;         if (c0 >= 0) v = __builtin_nontemporal_load(W + (size_t)(k0 + kk) * ldw + c0 + (lane & 31));
;         if (kscale) v *= kscale[k0 + kk];
;         scr[kk * 33 + (lane & 31)] = v; }
; __global__ void __launch_bounds__(512, 2) mega_fwd(Args a) {
;     ...
;             if (r < I_UQ) { const int kb = r / 24, nb = r % 24, pn = nb >> 3, bj = (nb >> 2) & 1, wc = nb & 3;
;                 const int c0 = pn < 2 ? 96 * (4 * pn + wc) + 32 * bj : 96 * (4 * bj + wc) + 64;
;                 p0_transpose_item(w_uq, 768, c0, kb * 64, Wt_uq, 384, nb * 32, q_norm_g, scr, lane); continue; } r -= I_UQ;
.LBB0_64:
	s_and_b32 s0, 0xffff, s11
	s_lshl_b32 s11, s0, 6
	s_and_b64 vcc, exec, s[16:17]
	s_cbranch_vccz .Lp0_uq_noks
	v_mbcnt_lo_u32_b32 v4, -1, 0
	v_mbcnt_hi_u32_b32 v4, -1, v4
	v_and_b32_e32 v4, 7, v4
	v_lshlrev_b32_e32 v4, 5, v4
	s_lshl_b32 s0, s11, 2
	v_add_u32_e32 v105, s0, v4
	global_load_dwordx4 v[146:149], v105, s[60:61]
	global_load_dwordx4 v[150:153], v105, s[60:61] offset:16
.Lp0_uq_ksdone:
	v_or_b32_e32 v106, s11, v43
	v_mul_u32_u24_e32 v4, 0x300, v106
	v_lshl_add_u64 v[40:41], s[4:5], 2, v[24:25]
	v_lshlrev_b32_e32 v4, 2, v4
	v_lshl_add_u64 v[40:41], v[40:41], 0, v[4:5]
	s_movk_i32 s4, 0x1800
	global_load_dword v113, v[40:41], off nt
	v_lshl_add_u64 v[108:109], v[40:41], 0, s[4:5]
	s_add_i32 s4, s4, 0x1800
	global_load_dword v114, v[108:109], off nt
	v_lshl_add_u64 v[110:111], v[40:41], 0, s[4:5]
	s_add_i32 s4, s4, 0x1800
	global_load_dword v115, v[110:111], off nt
	v_lshl_add_u64 v[106:107], v[40:41], 0, s[4:5]
	s_add_i32 s4, s4, 0x1800
	global_load_dword v116, v[106:107], off nt
	v_lshl_add_u64 v[108:109], v[40:41], 0, s[4:5]
	s_add_i32 s4, s4, 0x1800
	global_load_dword v117, v[108:109], off nt
	v_lshl_add_u64 v[110:111], v[40:41], 0, s[4:5]
	s_add_i32 s4, s4, 0x1800
	global_load_dword v118, v[110:111], off nt
	v_lshl_add_u64 v[106:107], v[40:41], 0, s[4:5]
	s_add_i32 s4, s4, 0x1800
	global_load_dword v119, v[106:107], off nt
	v_lshl_add_u64 v[108:109], v[40:41], 0, s[4:5]
	s_add_i32 s4, s4, 0x1800
	global_load_dword v120, v[108:109], off nt
	v_lshl_add_u64 v[110:111], v[40:41], 0, s[4:5]
	s_add_i32 s4, s4, 0x1800
	global_load_dword v121, v[110:111], off nt
	v_lshl_add_u64 v[106:107], v[40:41], 0, s[4:5]
	s_add_i32 s4, s4, 0x1800
	global_load_dword v122, v[106:107], off nt
	v_lshl_add_u64 v[108:109], v[40:41], 0, s[4:5]
	s_add_i32 s4, s4, 0x1800
	global_load_dword v123, v[108:109], off nt
	v_lshl_add_u64 v[110:111], v[40:41], 0, s[4:5]
	s_add_i32 s4, s4, 0x1800
	global_load_dword v124, v[110:111], off nt
	v_lshl_add_u64 v[106:107], v[40:41], 0, s[4:5]
	s_add_i32 s4, s4, 0x1800
	global_load_dword v125, v[106:107], off nt
	v_lshl_add_u64 v[108:109], v[40:41], 0, s[4:5]
	s_add_i32 s4, s4, 0x1800
	global_load_dword v126, v[108:109], off nt
	v_lshl_add_u64 v[110:111], v[40:41], 0, s[4:5]
	s_add_i32 s4, s4, 0x1800
	global_load_dword v127, v[110:111], off nt
	v_lshl_add_u64 v[106:107], v[40:41], 0, s[4:5]
	s_add_i32 s4, s4, 0x1800
	global_load_dword v128, v[106:107], off nt
	v_lshl_add_u64 v[108:109], v[40:41], 0, s[4:5]
	s_add_i32 s4, s4, 0x1800
	global_load_dword v129, v[108:109], off nt
	v_lshl_add_u64 v[110:111], v[40:41], 0, s[4:5]
	s_add_i32 s4, s4, 0x1800
	global_load_dword v130, v[110:111], off nt
	v_lshl_add_u64 v[106:107], v[40:41], 0, s[4:5]
	s_add_i32 s4, s4, 0x1800
	global_load_dword v131, v[106:107], off nt
	v_lshl_add_u64 v[108:109], v[40:41], 0, s[4:5]
	s_add_i32 s4, s4, 0x1800
	global_load_dword v132, v[108:109], off nt
	v_lshl_add_u64 v[110:111], v[40:41], 0, s[4:5]
	s_add_i32 s4, s4, 0x1800
	global_load_dword v133, v[110:111], off nt
	v_lshl_add_u64 v[106:107], v[40:41], 0, s[4:5]
	s_add_i32 s4, s4, 0x1800
	global_load_dword v134, v[106:107], off nt
	v_lshl_add_u64 v[108:109], v[40:41], 0, s[4:5]
	s_add_i32 s4, s4, 0x1800
	global_load_dword v135, v[108:109], off nt
	v_lshl_add_u64 v[110:111], v[40:41], 0, s[4:5]
	s_add_i32 s4, s4, 0x1800
	global_load_dword v136, v[110:111], off nt
	v_lshl_add_u64 v[106:107], v[40:41], 0, s[4:5]
	s_add_i32 s4, s4, 0x1800
	global_load_dword v137, v[106:107], off nt
	v_lshl_add_u64 v[108:109], v[40:41], 0, s[4:5]
	s_add_i32 s4, s4, 0x1800
	global_load_dword v138, v[108:109], off nt
	v_lshl_add_u64 v[110:111], v[40:41], 0, s[4:5]
	s_add_i32 s4, s4, 0x1800
	global_load_dword v139, v[110:111], off nt
	v_lshl_add_u64 v[106:107], v[40:41], 0, s[4:5]
	s_add_i32 s4, s4, 0x1800
	global_load_dword v140, v[106:107], off nt
	v_lshl_add_u64 v[108:109], v[40:41], 0, s[4:5]
	s_add_i32 s4, s4, 0x1800
	global_load_dword v141, v[108:109], off nt
	v_lshl_add_u64 v[110:111], v[40:41], 0, s[4:5]
	s_add_i32 s4, s4, 0x1800
	global_load_dword v142, v[110:111], off nt
	v_lshl_add_u64 v[106:107], v[40:41], 0, s[4:5]
	s_add_i32 s4, s4, 0x1800
	global_load_dword v143, v[106:107], off nt
	v_lshl_add_u64 v[108:109], v[40:41], 0, s[4:5]
	global_load_dword v144, v[108:109], off nt
	v_add_u32_e32 v41, v44, v45
	s_waitcnt vmcnt(30)
	ds_write2_b32 v41, v113, v114 offset1:66
	s_waitcnt vmcnt(28)
	ds_write2_b32 v41, v115, v116 offset0:132 offset1:198
	v_add_u32_e32 v41, 0x400, v41
	s_waitcnt vmcnt(26)
	ds_write2_b32 v41, v117, v118 offset0:8 offset1:74
	v_add_u32_e32 v41, v44, v52
	s_waitcnt vmcnt(24)
	ds_write2_b32 v41, v119, v120 offset1:66
	s_waitcnt vmcnt(22)
	ds_write2_b32 v41, v121, v122 offset0:132 offset1:198
	v_add_u32_e32 v41, 0x400, v41
	s_waitcnt vmcnt(20)
; #define LAS __attribute__((address_space(3)))
; __device__ __forceinline__ unsigned cvt_pk_bf16(float lo, float hi) { unsigned r; asm("v_cvt_pk_bf16_f32 %0, %1, %2" : "=v"(r) : "v"(lo), "v"(hi)); return r; }
; #define LDS_WAIT() asm volatile("s_waitcnt lgkmcnt(0)" ::: "memory")
; __device__ __forceinline__ void p0_transpose_item(const float* W, int ldw, int c0, int k0, bf16_t* WT, int K, int n0, const float* kscale, LAS float* scr, int lane) {
; #pragma unroll
;     for (int i = 0; i < 32; ++i) { const int kk = 2 * i + (lane >> 5); float v = 0.f;
;         if (c0 >= 0) v = __builtin_nontemporal_load(W + (size_t)(k0 + kk) * ldw + c0 + (lane & 31));
;         if (kscale) v *= kscale[k0 + kk];
;         scr[kk * 33 + (lane & 31)] = v; }
;     LDS_WAIT(); asm volatile("" ::: "memory");
;     const int c = lane & 7;
; #pragma unroll
;     for (int j = 0; j < 4; ++j) { const int n = (lane >> 3) + 8 * j; const LAS float* s = scr + (8 * c) * 33 + n;
;         u32x4 o; o.x = cvt_pk_bf16(s[0 * 33], s[1 * 33]); o.y = cvt_pk_bf16(s[2 * 33], s[3 * 33]); o.z = cvt_pk_bf16(s[4 * 33], s[5 * 33]); o.w = cvt_pk_bf16(s[6 * 33], s[7 * 33]);
;         *(u32x4*)(WT + (size_t)(n0 + n) * K + k0 + 8 * c) = o; }
;     LDS_WAIT(); asm volatile("" ::: "memory");
	ds_write2_b32 v41, v123, v124 offset0:8 offset1:74
	v_add_u32_e32 v41, v44, v55
	s_waitcnt vmcnt(18)
	ds_write2_b32 v41, v125, v126 offset1:66
	s_waitcnt vmcnt(16)
	ds_write2_b32 v41, v127, v128 offset0:132 offset1:198
	v_add_u32_e32 v41, 0x400, v41
	s_waitcnt vmcnt(14)
	ds_write2_b32 v41, v129, v130 offset0:8 offset1:74
	v_add_u32_e32 v41, v44, v58
	s_waitcnt vmcnt(12)
	ds_write2_b32 v41, v131, v132 offset1:66
	s_waitcnt vmcnt(10)
	ds_write2_b32 v41, v133, v134 offset0:132 offset1:198
	v_add_u32_e32 v41, 0x400, v41
	s_waitcnt vmcnt(8)
	ds_write2_b32 v41, v135, v136 offset0:8 offset1:74
	v_add_u32_e32 v41, v44, v61
	s_waitcnt vmcnt(6)
	ds_write2_b32 v41, v137, v138 offset1:66
	s_waitcnt vmcnt(4)
	ds_write2_b32 v41, v139, v140 offset0:132 offset1:198
	v_add_u32_e32 v41, 0x400, v41
	s_waitcnt vmcnt(2)
	ds_write2_b32 v41, v141, v142 offset0:8 offset1:74
	s_waitcnt vmcnt(0)
	ds_write2_b32 v41, v143, v144 offset0:140 offset1:206
	s_lshl_b32 s0, s10, 5
	s_waitcnt lgkmcnt(0)
	v_or_b32_e32 v4, s0, v42
	s_lshl_b32 s4, s11, 1
	ds_read2_b32 v[40:41], v62 offset0:33 offset1:41
	ds_read2_b32 v[110:111], v62 offset1:8
	ds_read2_b32 v[112:113], v62 offset0:66 offset1:74
	ds_read2_b32 v[114:115], v62 offset0:99 offset1:107
	ds_read2_b32 v[116:117], v62 offset0:132 offset1:140
	ds_read2_b32 v[118:119], v62 offset0:165 offset1:173
	ds_read2_b32 v[120:121], v62 offset0:198 offset1:206
	ds_read2_b32 v[122:123], v62 offset0:231 offset1:239
	v_mul_u32_u24_e32 v4, 0x180, v4
	v_lshl_add_u64 v[124:125], v[36:37], 0, s[4:5]
	v_lshlrev_b32_e32 v4, 1, v4
	v_lshl_add_u64 v[126:127], v[124:125], 0, v[4:5]
	v_or_b32_e32 v4, s0, v102
	v_mul_u32_u24_e32 v4, 0x180, v4
	s_waitcnt lgkmcnt(6)
	v_mul_f32_e32 v110, v110, v146
	v_mul_f32_e32 v40, v40, v147
	v_mul_f32_e32 v111, v111, v146
	v_mul_f32_e32 v41, v41, v147
	v_cvt_pk_bf16_f32 v106, v110, v40
	v_lshlrev_b32_e32 v4, 1, v4
	s_waitcnt lgkmcnt(4)
	v_mul_f32_e32 v112, v112, v148
	v_mul_f32_e32 v114, v114, v149
	v_mul_f32_e32 v113, v113, v148
	v_mul_f32_e32 v115, v115, v149
	v_cvt_pk_bf16_f32 v107, v112, v114
	s_waitcnt lgkmcnt(2)
	v_mul_f32_e32 v116, v116, v150
	v_mul_f32_e32 v118, v118, v151
	v_mul_f32_e32 v117, v117, v150
	v_mul_f32_e32 v119, v119, v151
	v_cvt_pk_bf16_f32 v108, v116, v118
	s_waitcnt lgkmcnt(0)
	v_mul_f32_e32 v120, v120, v152
	v_mul_f32_e32 v122, v122, v153
	v_mul_f32_e32 v121, v121, v152
	v_mul_f32_e32 v123, v123, v153
	v_cvt_pk_bf16_f32 v109, v120, v122
	global_store_dwordx4 v[126:127], v[106:109], off
	s_nop 1
	v_cvt_pk_bf16_f32 v106, v111, v41
	v_lshl_add_u64 v[40:41], v[124:125], 0, v[4:5]
	v_or_b32_e32 v4, s0, v103
	v_cvt_pk_bf16_f32 v107, v113, v115
	v_cvt_pk_bf16_f32 v108, v117, v119
	v_cvt_pk_bf16_f32 v109, v121, v123
	ds_read2_b32 v[110:111], v62 offset0:16 offset1:24
	ds_read2_b32 v[112:113], v62 offset0:49 offset1:57
	ds_read2_b32 v[114:115], v62 offset0:82 offset1:90
	ds_read2_b32 v[116:117], v62 offset0:115 offset1:123
	ds_read2_b32 v[118:119], v62 offset0:148 offset1:156
	ds_read2_b32 v[120:121], v62 offset0:181 offset1:189
	ds_read2_b32 v[122:123], v62 offset0:214 offset1:222
	ds_read2_b32 v[126:127], v62 offset0:247 offset1:255
	v_mul_u32_u24_e32 v4, 0x180, v4
	v_lshlrev_b32_e32 v4, 1, v4
	global_store_dwordx4 v[40:41], v[106:109], off
	v_lshl_add_u64 v[40:41], v[124:125], 0, v[4:5]
	v_or_b32_e32 v4, s0, v104
	v_mul_u32_u24_e32 v4, 0x180, v4
	v_lshlrev_b32_e32 v4, 1, v4
	s_waitcnt lgkmcnt(6)
	v_mul_f32_e32 v110, v110, v146
	v_mul_f32_e32 v112, v112, v147
	v_mul_f32_e32 v111, v111, v146
	v_mul_f32_e32 v113, v113, v147
	v_cvt_pk_bf16_f32 v106, v110, v112
	s_waitcnt lgkmcnt(4)
	v_mul_f32_e32 v114, v114, v148
	v_mul_f32_e32 v116, v116, v149
	v_mul_f32_e32 v115, v115, v148
	v_mul_f32_e32 v117, v117, v149
	v_cvt_pk_bf16_f32 v107, v114, v116
	s_waitcnt lgkmcnt(2)
	v_mul_f32_e32 v118, v118, v150
	v_mul_f32_e32 v120, v120, v151
	v_mul_f32_e32 v119, v119, v150
	v_mul_f32_e32 v121, v121, v151
	v_cvt_pk_bf16_f32 v108, v118, v120
	s_waitcnt lgkmcnt(0)
	v_mul_f32_e32 v122, v122, v152
	v_mul_f32_e32 v126, v126, v153
	v_mul_f32_e32 v123, v123, v152
	v_mul_f32_e32 v127, v127, v153
	v_cvt_pk_bf16_f32 v109, v122, v126
	global_store_dwordx4 v[40:41], v[106:109], off
	v_lshl_add_u64 v[40:41], v[124:125], 0, v[4:5]
	s_nop 0
	v_cvt_pk_bf16_f32 v106, v111, v113
	v_cvt_pk_bf16_f32 v107, v115, v117
	v_cvt_pk_bf16_f32 v108, v119, v121
	v_cvt_pk_bf16_f32 v109, v123, v127
	global_store_dwordx4 v[40:41], v[106:109], off
	s_waitcnt lgkmcnt(0)
	s_branch .LBB0_130
.Lp0_uq_noks:
	v_mov_b32_e32 v146, 1.0
	v_mov_b32_e32 v147, 1.0
	v_mov_b32_e32 v148, 1.0
	v_mov_b32_e32 v149, 1.0
	v_mov_b32_e32 v150, 1.0
	v_mov_b32_e32 v151, 1.0
	v_mov_b32_e32 v152, 1.0
	v_mov_b32_e32 v153, 1.0
	s_branch .Lp0_uq_ksdone

; #define LAS __attribute__((address_space(3)))
; __device__ __forceinline__ void p0_transpose_item(const float* W, int ldw, int c0, int k0, bf16_t* WT, int K, int n0, const float* kscale, LAS float* scr, int lane) {
; #pragma unroll
;     for (int i = 0; i < 32; ++i) { const int kk = 2 * i + (lane >> 5); float v = 0.f;
;         if (c0 >= 0) v = __builtin_nontemporal_load(W + (size_t)(k0 + kk) * ldw + c0 + (lane & 31));
;         if (kscale) v *= kscale[k0 + kk];
;         scr[kk * 33 + (lane & 31)] = v; }
; __global__ void __launch_bounds__(512, 2) mega_fwd(Args a) {
;     ...
;             if (r < I_IN) { const int kb = r / 56, nb = r % 56, n0 = nb * 32;
;                 const int c0 = n0 < 512 ? n0 : n0 < 768 ? 1408 + (n0 - 512) : n0 < 1152 ? 1024 + (n0 - 768) : n0 < 1184 ? 1664 : n0 < 1280 ? -1 : 512 + (n0 - 1280);
;                 p0_transpose_item(w_in, 1696, c0, kb * 64, Wt_in, 1024, n0, nullptr, scr, lane); continue; } r -= I_IN;
.LBB0_141:
	s_lshl_b32 s0, s36, 6
	s_cmp_lt_i32 s4, 0
	s_cbranch_scc1 .Lp0_in_zero
	v_or_b32_e32 v105, s0, v43
	v_lshl_add_u64 v[40:41], s[4:5], 2, v[26:27]
	v_mad_i64_i32 v[40:41], s[10:11], v105, s54, v[40:41]
	s_movk_i32 s4, 0x3500
	global_load_dword v113, v[40:41], off nt
	v_lshl_add_u64 v[108:109], v[40:41], 0, s[4:5]
	s_add_i32 s4, s4, 0x3500
	global_load_dword v114, v[108:109], off nt
	v_lshl_add_u64 v[110:111], v[40:41], 0, s[4:5]
	s_add_i32 s4, s4, 0x3500
	global_load_dword v115, v[110:111], off nt
	v_lshl_add_u64 v[106:107], v[40:41], 0, s[4:5]
	s_add_i32 s4, s4, 0x3500
	global_load_dword v116, v[106:107], off nt
	v_lshl_add_u64 v[108:109], v[40:41], 0, s[4:5]
	s_add_i32 s4, s4, 0x3500
	global_load_dword v117, v[108:109], off nt
	v_lshl_add_u64 v[110:111], v[40:41], 0, s[4:5]
	s_add_i32 s4, s4, 0x3500
	global_load_dword v118, v[110:111], off nt
	v_lshl_add_u64 v[106:107], v[40:41], 0, s[4:5]
	s_add_i32 s4, s4, 0x3500
	global_load_dword v119, v[106:107], off nt
	v_lshl_add_u64 v[108:109], v[40:41], 0, s[4:5]
	s_add_i32 s4, s4, 0x3500
	global_load_dword v120, v[108:109], off nt
	v_lshl_add_u64 v[110:111], v[40:41], 0, s[4:5]
	s_add_i32 s4, s4, 0x3500
	global_load_dword v121, v[110:111], off nt
	v_lshl_add_u64 v[106:107], v[40:41], 0, s[4:5]
	s_add_i32 s4, s4, 0x3500
	global_load_dword v122, v[106:107], off nt
	v_lshl_add_u64 v[108:109], v[40:41], 0, s[4:5]
	s_add_i32 s4, s4, 0x3500
	global_load_dword v123, v[108:109], off nt
	v_lshl_add_u64 v[110:111], v[40:41], 0, s[4:5]
	s_add_i32 s4, s4, 0x3500
	global_load_dword v124, v[110:111], off nt
	v_lshl_add_u64 v[106:107], v[40:41], 0, s[4:5]
	s_add_i32 s4, s4, 0x3500
	global_load_dword v125, v[106:107], off nt
	v_lshl_add_u64 v[108:109], v[40:41], 0, s[4:5]
	s_add_i32 s4, s4, 0x3500
	global_load_dword v126, v[108:109], off nt
	v_lshl_add_u64 v[110:111], v[40:41], 0, s[4:5]
	s_add_i32 s4, s4, 0x3500
	global_load_dword v127, v[110:111], off nt
	v_lshl_add_u64 v[106:107], v[40:41], 0, s[4:5]
	s_add_i32 s4, s4, 0x3500
	global_load_dword v128, v[106:107], off nt
	v_lshl_add_u64 v[108:109], v[40:41], 0, s[4:5]
	s_add_i32 s4, s4, 0x3500
	global_load_dword v129, v[108:109], off nt
	v_lshl_add_u64 v[110:111], v[40:41], 0, s[4:5]
	s_add_i32 s4, s4, 0x3500
	global_load_dword v130, v[110:111], off nt
	v_lshl_add_u64 v[106:107], v[40:41], 0, s[4:5]
	s_add_i32 s4, s4, 0x3500
	global_load_dword v131, v[106:107], off nt
	v_lshl_add_u64 v[108:109], v[40:41], 0, s[4:5]
	s_add_i32 s4, s4, 0x3500
	global_load_dword v132, v[108:109], off nt
	v_lshl_add_u64 v[110:111], v[40:41], 0, s[4:5]
	s_add_i32 s4, s4, 0x3500
	global_load_dword v133, v[110:111], off nt
	v_lshl_add_u64 v[106:107], v[40:41], 0, s[4:5]
	s_add_i32 s4, s4, 0x3500
	global_load_dword v134, v[106:107], off nt
	v_lshl_add_u64 v[108:109], v[40:41], 0, s[4:5]
	s_add_i32 s4, s4, 0x3500
	global_load_dword v135, v[108:109], off nt
	v_lshl_add_u64 v[110:111], v[40:41], 0, s[4:5]
	s_add_i32 s4, s4, 0x3500
	global_load_dword v136, v[110:111], off nt
	v_lshl_add_u64 v[106:107], v[40:41], 0, s[4:5]
	s_add_i32 s4, s4, 0x3500
	global_load_dword v137, v[106:107], off nt
	v_lshl_add_u64 v[108:109], v[40:41], 0, s[4:5]
	s_add_i32 s4, s4, 0x3500
	global_load_dword v138, v[108:109], off nt
	v_lshl_add_u64 v[110:111], v[40:41], 0, s[4:5]
	s_add_i32 s4, s4, 0x3500
	global_load_dword v139, v[110:111], off nt
	v_lshl_add_u64 v[106:107], v[40:41], 0, s[4:5]
	s_add_i32 s4, s4, 0x3500
	global_load_dword v140, v[106:107], off nt
	v_lshl_add_u64 v[108:109], v[40:41], 0, s[4:5]
	s_add_i32 s4, s4, 0x3500
	global_load_dword v141, v[108:109], off nt
	v_lshl_add_u64 v[110:111], v[40:41], 0, s[4:5]
	s_add_i32 s4, s4, 0x3500
	global_load_dword v142, v[110:111], off nt
	v_lshl_add_u64 v[106:107], v[40:41], 0, s[4:5]
	s_add_i32 s4, s4, 0x3500
	global_load_dword v143, v[106:107], off nt
	v_lshl_add_u64 v[108:109], v[40:41], 0, s[4:5]
	global_load_dword v144, v[108:109], off nt
	v_add_u32_e32 v41, v44, v45
	s_waitcnt vmcnt(30)
	ds_write2_b32 v41, v113, v114 offset1:66
	s_waitcnt vmcnt(28)
	ds_write2_b32 v41, v115, v116 offset0:132 offset1:198
	v_add_u32_e32 v41, 0x400, v41
	s_waitcnt vmcnt(26)
	ds_write2_b32 v41, v117, v118 offset0:8 offset1:74
	v_add_u32_e32 v41, v44, v52
	s_waitcnt vmcnt(24)
	ds_write2_b32 v41, v119, v120 offset1:66
	s_waitcnt vmcnt(22)
	ds_write2_b32 v41, v121, v122 offset0:132 offset1:198
	v_add_u32_e32 v41, 0x400, v41
	s_waitcnt vmcnt(20)
	ds_write2_b32 v41, v123, v124 offset0:8 offset1:74
	v_add_u32_e32 v41, v44, v55
	s_waitcnt vmcnt(18)
	ds_write2_b32 v41, v125, v126 offset1:66
	s_waitcnt vmcnt(16)
	ds_write2_b32 v41, v127, v128 offset0:132 offset1:198
	v_add_u32_e32 v41, 0x400, v41
	s_waitcnt vmcnt(14)
	ds_write2_b32 v41, v129, v130 offset0:8 offset1:74
	v_add_u32_e32 v41, v44, v58
	s_waitcnt vmcnt(12)
	ds_write2_b32 v41, v131, v132 offset1:66
	s_waitcnt vmcnt(10)
	ds_write2_b32 v41, v133, v134 offset0:132 offset1:198
	v_add_u32_e32 v41, 0x400, v41
	s_waitcnt vmcnt(8)
	ds_write2_b32 v41, v135, v136 offset0:8 offset1:74
	v_add_u32_e32 v41, v44, v61
	s_waitcnt vmcnt(6)
	ds_write2_b32 v41, v137, v138 offset1:66
	s_waitcnt vmcnt(4)
	ds_write2_b32 v41, v139, v140 offset0:132 offset1:198
	v_add_u32_e32 v41, 0x400, v41
	s_waitcnt vmcnt(2)
	ds_write2_b32 v41, v141, v142 offset0:8 offset1:74
	s_waitcnt vmcnt(0)
	ds_write2_b32 v41, v143, v144 offset0:140 offset1:206
	s_branch .LBB0_20
; #define LAS __attribute__((address_space(3)))
; __device__ __forceinline__ void p0_transpose_item(const float* W, int ldw, int c0, int k0, bf16_t* WT, int K, int n0, const float* kscale, LAS float* scr, int lane) {
; #pragma unroll
;     for (int i = 0; i < 32; ++i) { const int kk = 2 * i + (lane >> 5); float v = 0.f;
;         if (c0 >= 0) v = __builtin_nontemporal_load(W + (size_t)(k0 + kk) * ldw + c0 + (lane & 31));
;         if (kscale) v *= kscale[k0 + kk];
;         scr[kk * 33 + (lane & 31)] = v; }
.Lp0_in_zero:
	v_mov_b32_e32 v113, 0
	v_mov_b32_e32 v114, 0
	v_mov_b32_e32 v115, 0
	v_mov_b32_e32 v116, 0
	v_mov_b32_e32 v117, 0
	v_mov_b32_e32 v118, 0
	v_mov_b32_e32 v119, 0
	v_mov_b32_e32 v120, 0
	v_mov_b32_e32 v121, 0
	v_mov_b32_e32 v122, 0
	v_mov_b32_e32 v123, 0
	v_mov_b32_e32 v124, 0
	v_mov_b32_e32 v125, 0
	v_mov_b32_e32 v126, 0
	v_mov_b32_e32 v127, 0
	v_mov_b32_e32 v128, 0
	v_mov_b32_e32 v129, 0
	v_mov_b32_e32 v130, 0
	v_mov_b32_e32 v131, 0
	v_mov_b32_e32 v132, 0
	v_mov_b32_e32 v133, 0
	v_mov_b32_e32 v134, 0
	v_mov_b32_e32 v135, 0
	v_mov_b32_e32 v136, 0
	v_mov_b32_e32 v137, 0
	v_mov_b32_e32 v138, 0
	v_mov_b32_e32 v139, 0
	v_mov_b32_e32 v140, 0
	v_mov_b32_e32 v141, 0
	v_mov_b32_e32 v142, 0
	v_mov_b32_e32 v143, 0
	v_mov_b32_e32 v144, 0
	v_add_u32_e32 v41, v44, v45
	ds_write2_b32 v41, v113, v114 offset1:66
	ds_write2_b32 v41, v115, v116 offset0:132 offset1:198
	v_add_u32_e32 v41, 0x400, v41
	ds_write2_b32 v41, v117, v118 offset0:8 offset1:74
	v_add_u32_e32 v41, v44, v52
	ds_write2_b32 v41, v119, v120 offset1:66
	ds_write2_b32 v41, v121, v122 offset0:132 offset1:198
	v_add_u32_e32 v41, 0x400, v41
	ds_write2_b32 v41, v123, v124 offset0:8 offset1:74
	v_add_u32_e32 v41, v44, v55
	ds_write2_b32 v41, v125, v126 offset1:66
	ds_write2_b32 v41, v127, v128 offset0:132 offset1:198
	v_add_u32_e32 v41, 0x400, v41
	ds_write2_b32 v41, v129, v130 offset0:8 offset1:74
	v_add_u32_e32 v41, v44, v58
	ds_write2_b32 v41, v131, v132 offset1:66
	ds_write2_b32 v41, v133, v134 offset0:132 offset1:198
	v_add_u32_e32 v41, 0x400, v41
	ds_write2_b32 v41, v135, v136 offset0:8 offset1:74
	v_add_u32_e32 v41, v44, v61
	ds_write2_b32 v41, v137, v138 offset1:66
	ds_write2_b32 v41, v139, v140 offset0:132 offset1:198
	v_add_u32_e32 v41, 0x400, v41
	ds_write2_b32 v41, v141, v142 offset0:8 offset1:74
	ds_write2_b32 v41, v143, v144 offset0:140 offset1:206
	s_branch .LBB0_20
